# DIFF attention: removed QK MFMA steps and K-fragment LDS reads for the zero-padded head-dim half (dims 64..127 are exact zeros)
# speedup vs baseline: 1.0221x; 1.0026x over previous
; __device__ __forceinline__ int ltid() { int t = __builtin_amdgcn_workitem_id_x(); asm volatile("" : "+v"(t)); return t; }
; __device__ __forceinline__ int v_st(int k, int c) { const int kk = (k & ~0xC) | ((k & 4) << 1) | ((k & 8) >> 1); return ((kk >> 3) * 4 + (c >> 5)) * 512 + ((kk & 7) * 32 + (c & 31)) * 2; }
; __device__ __forceinline__ int v_rd_base(int lane) { return ((lane & 3) << 3) | (((lane >> 2) & 3) << 6) | (((lane >> 4) & 1) << 5) | (((lane >> 5) & 1) << 8); }
; #define AB_SLOAD(Z, k0) do { sZ##_dummy: ; } while (0)
; __device__ __forceinline__ void qkt(f32x16& p0, f32x16& p1, const char* Ks, const bf16x8* qr, int r32, int hi) {
;   p0 = f32x16{}; p1 = f32x16{};
; #pragma unroll
;   for (int d0 = 0; d0 < 8; ++d0) { const int cb = (d0 * 16 + hi * 8) * 2;
;     const bf16x8 b0 = *reinterpret_cast<const bf16x8*>(Ks + AB_KSWZ(r32, cb));
;     const bf16x8 b1 = *reinterpret_cast<const bf16x8*>(Ks + AB_KSWZ(32 + r32, cb));
;     p0 = __builtin_amdgcn_mfma_f32_32x32x16_bf16(b0, qr[d0], p0, 0, 0, 0);
;     p1 = __builtin_amdgcn_mfma_f32_32x32x16_bf16(b1, qr[d0], p1, 0, 0, 0); }
; }
; template <bool OUT_BF16>
; __device__ __forceinline__ void attn_body(const bf16_t* __restrict__ Qb, int ldq, const bf16_t* __restrict__ Kh, const bf16_t* __restrict__ Vh, void* __restrict__ Ob, int ldo, int seq, char* lds) {
;   const int tid = ltid(), wid = tid >> 6, lane = tid & 63, r32 = lane & 31, hi = lane >> 5;
;   char* V_lds = lds; char* K_lds = lds + 2 * SHM_V;
;   float* wsf = (float*)(lds + 2 * SHM_V + 2 * SHM_K) + wid * 64; float* li_l = wsf; float* al_l = wsf + 32;
;   float m_reg = -1e30f, l_reg = 0; f32x16 o[4] = {}; bf16x8 qr[8];
;   const bf16_t* Qw = Qb + (long)(wid * QBLK + r32) * ldq + hi * 8;
; #pragma unroll
;   for (int d0 = 0; d0 < 8; ++d0) qr[d0] = *reinterpret_cast<const bf16x8*>(Qw + d0 * 16);
;   const int sr = tid >> 4, sc = (tid & 15) * 8, vst0 = v_st(sr, sc), vst1 = v_st(32 + sr, sc);
;   const int vb0 = (int)(uintptr_t)V_lds + v_rd_base(lane);
;   bf16x8 sA_vs0, sA_vs1, sA_ks0, sA_ks1, sB_vs0, sB_vs1, sB_ks0, sB_ks1;
;     ...
;   f32x16 pA0, pA1, pB0, pB1; float mnA, mnB, alA, alB; bf16x8 pa0, pa1, pa2, pa3; const int NT = seq / KVBLK;
;   __syncthreads();
;   AB_SLOAD(A, 0); asm volatile("s_waitcnt vmcnt(0)" ::: "memory"); AB_SWRITE(0, A); __syncthreads();
;   qkt(pA0, pA1, K_lds, qr, r32, hi); partialSM(pA0, pA1, m_reg, mnA, alA);
.LBB0_269:
	s_and_b32 s3, s16, 7
	s_lshl_b64 s[10:11], s[40:41], 11
	s_add_u32 s4, s69, s10
	s_addc_u32 s5, s75, s11
	s_lshl_b32 s7, s3, 8
	s_add_u32 s20, s4, s7
	v_mov_b32_e32 v74, v228
	s_addc_u32 s21, s5, 0
	s_lshl_b32 s4, s6, 3
	s_movk_i32 s15, 0xffe0
	v_ashrrev_i32_e32 v52, 1, v74
	s_or_b32 s12, s3, s4
	v_bfi_b32 v0, s15, v52, v74
	s_mul_hi_i32 s3, s12, 0x90000
	s_mul_i32 s12, s12, 0x90000
	v_ashrrev_i32_e32 v1, 31, v0
	s_add_u32 s4, s85, s12
	v_bfe_u32 v179, v74, 5, 1
	v_lshlrev_b64 v[0:1], 11, v[0:1]
	s_addc_u32 s5, s96, s3
	s_lshl_b32 s6, s6, 2
	s_bfe_u32 s17, s16, 0x20001
	v_lshl_add_u64 v[0:1], s[20:21], 0, v[0:1]
	v_lshlrev_b32_e32 v182, 4, v179
	v_mov_b32_e32 v183, v177
	s_waitcnt vmcnt(0)
	v_ashrrev_i32_e32 v16, 4, v74
	s_or_b32 s14, s17, s6
	v_lshl_add_u64 v[0:1], v[0:1], 0, v[182:183]
	v_lshlrev_b32_e32 v20, 3, v74
	v_add_u32_e32 v18, 32, v16
	s_mul_hi_i32 s13, s14, 0x90000
	s_mul_i32 s14, s14, 0x90000
	v_readlane_b32 s6, v254, 33
	global_load_dwordx4 v[124:127], v[0:1], off
	global_load_dwordx4 v[120:123], v[0:1], off offset:32
	global_load_dwordx4 v[116:119], v[0:1], off offset:64
	global_load_dwordx4 v[112:115], v[0:1], off offset:96
	global_load_dwordx4 v[108:111], v[0:1], off offset:128
	global_load_dwordx4 v[104:107], v[0:1], off offset:160
	global_load_dwordx4 v[100:103], v[0:1], off offset:192
	global_load_dwordx4 v[96:99], v[0:1], off offset:224
	v_and_b32_e32 v0, 0x78, v20
	v_ashrrev_i32_e32 v17, 31, v16
	v_ashrrev_i32_e32 v19, 31, v18
	s_add_u32 s6, s6, s14
	v_readlane_b32 s7, v254, 34
	v_lshlrev_b32_e32 v21, 1, v0
	v_lshlrev_b64 v[48:49], 8, v[16:17]
	v_lshlrev_b64 v[12:13], 8, v[18:19]
	s_addc_u32 s7, s7, s13
	v_or_b32_e32 v50, v48, v21
	v_mov_b32_e32 v51, v49
	v_or_b32_e32 v12, v12, v21
	v_lshl_add_u64 v[0:1], s[6:7], 0, v[50:51]
	v_lshl_add_u64 v[4:5], s[6:7], 0, v[12:13]
	s_barrier
	global_load_dwordx4 v[0:3], v[0:1], off
	s_nop 0
	global_load_dwordx4 v[4:7], v[4:5], off
	v_lshl_add_u64 v[8:9], s[4:5], 0, v[50:51]
	v_lshl_add_u64 v[12:13], s[4:5], 0, v[12:13]
	global_load_dwordx4 v[8:11], v[8:9], off
	v_and_b32_e32 v19, 0xfffff0, v16
	global_load_dwordx4 v[12:15], v[12:13], off
	v_lshlrev_b32_e32 v22, 1, v16
	v_lshrrev_b32_e32 v23, 1, v16
	v_and_b32_e32 v24, 3, v16
	v_and_or_b32 v19, v22, 8, v19
	v_and_or_b32 v22, v23, 4, v24
	v_and_b32_e32 v23, 0xfffff0, v18
	v_lshlrev_b32_e32 v24, 1, v18
	v_and_b32_e32 v17, 0x70, v74
	v_bfe_u32 v20, v20, 5, 2
	v_lshlrev_b32_e32 v16, 8, v16
	v_lshrrev_b32_e32 v19, 1, v19
	v_and_or_b32 v23, v24, 8, v23
	v_bitop3_b32 v16, v21, v16, v17 bitop3:0xde
	v_or_b32_e32 v19, v19, v20
	v_lshrrev_b32_e32 v23, 1, v23
	v_lshlrev_b32_e32 v22, 6, v22
	v_and_b32_e32 v25, 48, v21
	v_add_u32_e32 v198, 0, v16
	v_lshlrev_b32_e32 v16, 9, v19
	v_or_b32_e32 v19, v23, v20
	v_or3_b32 v16, v16, v22, v25
	v_lshlrev_b32_e32 v19, 9, v19
	v_lshlrev_b32_e32 v18, 8, v18
	v_or3_b32 v19, v19, v22, v25
	v_add_u32_e32 v199, 0, v16
	v_add_u32_e32 v200, 0, v19
	s_waitcnt vmcnt(0)
	v_and_b32_e32 v183, 31, v74
	v_lshlrev_b32_e32 v53, 4, v74
	s_add_i32 s15, 0, 0x10000
	s_mov_b64 s[20:21], 0x4000
	v_and_b32_e32 v192, 0xffffffe0, v52
	v_and_b32_e32 v75, 63, v74
	s_mov_b32 s22, 0x41380000
	s_mov_b64 s[24:25], 0x8000
	s_cmp_lg_u32 0, -1
	s_waitcnt vmcnt(3)
	ds_write_b128 v199, v[0:3]
	s_waitcnt vmcnt(2)
	ds_write_b128 v200, v[4:7]
	s_waitcnt vmcnt(1)
	ds_write_b128 v198, v[8:11] offset:32768
	v_bitop3_b32 v0, v21, v18, v17 bitop3:0xde
	v_add_u32_e32 v201, 0, v0
	s_mov_b32 s40, s41
	s_waitcnt vmcnt(0)
	ds_write_b128 v201, v[12:15] offset:32768
	v_lshlrev_b32_e32 v12, 8, v183
	v_and_b32_e32 v13, 0x70, v53
	v_bitop3_b32 v0, v182, v12, v13 bitop3:0xde
	v_add_u32_e32 v202, 0, v0
	s_waitcnt lgkmcnt(0)
	s_barrier
	ds_read_b128 v[0:3], v202 offset:32768
	ds_read_b128 v[4:7], v202 offset:40960
	s_waitcnt lgkmcnt(1)
	v_mfma_f32_32x32x16_bf16 v[16:31], v[0:3], v[124:127], 0
	v_or_b32_e32 v0, 32, v182
	v_bitop3_b32 v0, v0, v12, v13 bitop3:0xde
	v_add_u32_e32 v207, 0, v0
	v_and_b32_e32 v15, 0xc0, v53
	v_lshlrev_b32_e32 v14, 3, v75
	s_mov_b32 s42, s41
	s_mov_b32 s43, s41
	s_waitcnt lgkmcnt(0)
	v_mfma_f32_32x32x16_bf16 v[32:47], v[4:7], v[124:127], 0
	ds_read_b128 v[0:3], v207 offset:32768
	ds_read_b128 v[4:7], v207 offset:40960
	s_mov_b32 s44, s41
	s_mov_b32 s45, s41
	s_mov_b32 s46, s41
	s_mov_b32 s47, s41
	s_mov_b32 s48, s41
	s_mov_b32 s49, s41
	s_waitcnt lgkmcnt(1)
	v_mfma_f32_32x32x16_bf16 v[16:31], v[0:3], v[120:123], v[16:31]
	v_or_b32_e32 v0, 64, v182
	v_bitop3_b32 v0, v0, v12, v13 bitop3:0xde
	v_add_u32_e32 v206, 0, v0
	s_mov_b32 s50, s41
	s_mov_b32 s51, s41
	s_mov_b32 s52, s41
	s_mov_b32 s53, s41
	s_waitcnt lgkmcnt(0)
	v_mfma_f32_32x32x16_bf16 v[32:47], v[4:7], v[120:123], v[32:47]
	ds_read_b128 v[0:3], v206 offset:32768
	ds_read_b128 v[4:7], v206 offset:40960
	s_mov_b32 s54, s41
	s_mov_b32 s55, s41
	v_mov_b32_e32 v195, 0
	s_waitcnt lgkmcnt(1)
	v_mfma_f32_32x32x16_bf16 v[16:31], v[0:3], v[116:119], v[16:31]
	v_or_b32_e32 v0, 0x60, v182
	v_bitop3_b32 v0, v0, v12, v13 bitop3:0xde
	v_add_u32_e32 v205, 0, v0
	s_waitcnt lgkmcnt(0)
	v_mfma_f32_32x32x16_bf16 v[32:47], v[4:7], v[116:119], v[32:47]
	ds_read_b128 v[0:3], v205 offset:32768
	ds_read_b128 v[4:7], v205 offset:40960
	s_waitcnt lgkmcnt(1)
	v_mfma_f32_32x32x16_bf16 v[16:31], v[0:3], v[112:115], v[16:31]
	v_or_b32_e32 v0, 0x80, v182
	v_bitop3_b32 v0, v0, v12, v13 bitop3:0xde
	v_add_u32_e32 v204, 0, v0
	s_waitcnt lgkmcnt(0)
; __device__ __forceinline__ void partialSM(f32x16& p0, f32x16& p1, float& m_reg, float& mn, float& alpha) {
;   float pmax = p0[0];
; #pragma unroll
;   for (int r = 1; r < 16; ++r) pmax = fmaxf(pmax, p0[r]);
; #pragma unroll
;   for (int r = 0; r < 16; ++r) pmax = fmaxf(pmax, p1[r]);
;   { auto rr = __builtin_amdgcn_permlane32_swap(__float_as_uint(pmax), __float_as_uint(pmax), false, false);
;     pmax = fmaxf(__uint_as_float(rr[0]), __uint_as_float(rr[1])); }
;   if (__builtin_expect(__all(pmax - m_reg <= THR2), 1)) { mn = m_reg; alpha = 1.f; }
;   else { mn = fmaxf(m_reg, pmax); alpha = __builtin_amdgcn_exp2f(m_reg - mn); m_reg = mn; }
; #pragma unroll
;   for (int r = 0; r < 16; ++r) p0[r] = p0[r] - mn;
; #pragma unroll
;   for (int r = 0; r < 16; ++r) p1[r] = p1[r] - mn;
; #pragma unroll
;   for (int r = 0; r < 16; ++r) p0[r] = __builtin_amdgcn_exp2f(p0[r]);
; }
; __device__ __forceinline__ void qkt(f32x16& p0, f32x16& p1, const char* Ks, const bf16x8* qr, int r32, int hi) {
;   p0 = f32x16{}; p1 = f32x16{};
; #pragma unroll
;   for (int d0 = 0; d0 < 8; ++d0) { const int cb = (d0 * 16 + hi * 8) * 2;
;     const bf16x8 b0 = *reinterpret_cast<const bf16x8*>(Ks + AB_KSWZ(r32, cb));
;     const bf16x8 b1 = *reinterpret_cast<const bf16x8*>(Ks + AB_KSWZ(32 + r32, cb));
;     p0 = __builtin_amdgcn_mfma_f32_32x32x16_bf16(b0, qr[d0], p0, 0, 0, 0);
;     p1 = __builtin_amdgcn_mfma_f32_32x32x16_bf16(b1, qr[d0], p1, 0, 0, 0); }
; }
	v_mfma_f32_32x32x16_bf16 v[32:47], v[4:7], v[112:115], v[32:47]
	v_or_b32_e32 v0, 0xa0, v182
	v_bitop3_b32 v0, v0, v12, v13 bitop3:0xde
	v_add_u32_e32 v203, 0, v0
	v_and_b32_e32 v4, 0x3fffffc0, v74
	v_lshl_add_u32 v193, v4, 2, s15
	s_cselect_b32 s15, 0, 0
	v_lshl_add_u32 v194, v183, 2, v193
	v_lshl_add_u64 v[0:1], v[50:51], 0, s[20:21]
	s_mov_b64 s[20:21], 0x6000
	v_lshl_add_u64 v[2:3], s[6:7], 0, v[0:1]
	v_lshl_add_u64 v[8:9], v[50:51], 0, s[20:21]
	v_lshl_add_u64 v[0:1], s[4:5], 0, v[0:1]
	v_lshl_add_u64 v[10:11], s[6:7], 0, v[8:9]
	global_load_dwordx4 v[52:55], v[2:3], off
	global_load_dwordx4 v[56:59], v[10:11], off
	v_lshl_add_u64 v[2:3], s[4:5], 0, v[8:9]
	global_load_dwordx4 v[60:63], v[0:1], off
	global_load_dwordx4 v[64:67], v[2:3], off
	v_or_b32_e32 v0, 0xc0, v182
	v_bitop3_b32 v0, v0, v12, v13 bitop3:0xde
	v_add_u32_e32 v209, 0, v0
	v_lshlrev_b32_e32 v9, 1, v74
	v_and_or_b32 v8, v14, 24, v15
	v_and_b32_e32 v4, 32, v9
	v_and_b32_e32 v5, 0x100, v14
	v_or3_b32 v76, v8, v4, v5
	s_mov_b64 s[20:21], 0xa000
	v_add_u32_e32 v197, s15, v76
	v_or_b32_e32 v0, 0xe0, v182
	v_bitop3_b32 v0, v0, v12, v13 bitop3:0xde
	v_add_u32_e32 v208, 0, v0
	v_mov_b64_e32 v[0:1], s[40:41]
	v_mov_b64_e32 v[14:15], s[54:55]
	v_mov_b64_e32 v[2:3], s[42:43]
	v_mov_b64_e32 v[4:5], s[44:45]
	v_mov_b64_e32 v[6:7], s[46:47]
	v_mov_b64_e32 v[8:9], s[48:49]
	v_mov_b64_e32 v[10:11], s[50:51]
	s_nop 2
	v_max_f32_e32 v68, v17, v17
	v_max_f32_e32 v69, v16, v16
	v_max_f32_e32 v68, v69, v68
	v_max3_f32 v68, v68, v18, v19
	v_max3_f32 v68, v68, v20, v21
	v_max3_f32 v68, v68, v22, v23
	v_max3_f32 v68, v68, v24, v25
	v_max3_f32 v68, v68, v26, v27
	v_max3_f32 v68, v68, v28, v29
	v_max3_f32 v68, v68, v30, v31
	v_max3_f32 v68, v68, v32, v33
	v_max3_f32 v68, v68, v34, v35
	v_max3_f32 v68, v68, v36, v37
	v_max3_f32 v68, v68, v38, v39
	v_max3_f32 v68, v68, v40, v41
	v_max3_f32 v68, v68, v42, v43
	v_max3_f32 v68, v68, v44, v45
	v_max3_f32 v68, v68, v46, v47
	v_mov_b32_e32 v69, v68
	s_nop 1
	v_permlane32_swap_b32_e32 v68, v69
	v_max_f32_e32 v69, v69, v69
	v_max_f32_e32 v68, v68, v68
	v_max_f32_e32 v77, v68, v69
	v_add_f32_e32 v68, 0x7149f2ca, v77
	v_cmp_ge_f32_e32 vcc, s22, v68
	v_lshl_add_u64 v[68:69], v[50:51], 0, s[20:21]
	v_lshl_add_u64 v[70:71], s[4:5], 0, v[68:69]
	v_lshl_add_u64 v[50:51], v[50:51], 0, s[24:25]
	v_lshl_add_u64 v[68:69], s[6:7], 0, v[68:69]
	v_lshl_add_u64 v[72:73], s[4:5], 0, v[50:51]
	global_load_dwordx4 v[140:143], v[70:71], off
	global_load_dwordx4 v[136:139], v[72:73], off
	v_lshl_add_u64 v[50:51], s[6:7], 0, v[50:51]
	global_load_dwordx4 v[132:135], v[68:69], off
	global_load_dwordx4 v[128:131], v[50:51], off
	s_cmp_eq_u64 vcc, exec
	v_max_f32_e32 v50, 0xf149f2ca, v77
	s_cselect_b64 vcc, -1, 0
	v_cndmask_b32_e32 v168, v50, v233, vcc
	v_sub_f32_e32 v16, v16, v168
	v_exp_f32_e32 v161, v16
	v_sub_f32_e32 v16, v17, v168
	v_exp_f32_e32 v175, v16
	v_sub_f32_e32 v16, v18, v168
	v_exp_f32_e32 v162, v16
	v_sub_f32_e32 v16, v19, v168
	v_exp_f32_e32 v188, v16
	v_sub_f32_e32 v16, v20, v168
	v_exp_f32_e32 v174, v16
	v_sub_f32_e32 v16, v21, v168
	v_exp_f32_e32 v189, v16
	v_sub_f32_e32 v16, v22, v168
	v_exp_f32_e32 v163, v16
	v_sub_f32_e32 v16, v23, v168
	v_exp_f32_e32 v173, v16
	v_sub_f32_e32 v16, v24, v168
	s_waitcnt vmcnt(4)
	s_waitcnt vmcnt(7)
	ds_write_b128 v199, v[52:55] offset:16384
	s_waitcnt vmcnt(6)
	ds_write_b128 v200, v[56:59] offset:16384
	s_waitcnt vmcnt(5)
	ds_write_b128 v198, v[60:63] offset:49152
	s_waitcnt vmcnt(4)
	ds_write_b128 v201, v[64:67] offset:49152
	s_waitcnt lgkmcnt(0)
	s_barrier
	v_exp_f32_e32 v164, v16
	v_sub_f32_e32 v16, v25, v168
	s_load_dwordx2 s[20:21], s[94:95], 0xe0
	v_exp_f32_e32 v171, v16
	v_sub_f32_e32 v16, v26, v168
	v_exp_f32_e32 v165, v16
	v_sub_f32_e32 v16, v27, v168
	v_exp_f32_e32 v172, v16
	v_sub_f32_e32 v16, v28, v168
	v_sub_f32_e32 v156, v32, v168
	v_sub_f32_e32 v32, 0xf149f2ca, v50
	v_exp_f32_e32 v166, v16
	v_sub_f32_e32 v16, v29, v168
	s_addk_i32 s15, 0x4000
	v_exp_f32_e32 v32, v32
	v_exp_f32_e32 v169, v16
	v_sub_f32_e32 v16, v30, v168
	s_waitcnt lgkmcnt(0)
	s_add_u32 s4, s20, s14
	v_exp_f32_e32 v167, v16
	v_sub_f32_e32 v16, v31, v168
	s_addc_u32 s5, s21, s13
	v_exp_f32_e32 v170, v16
	v_lshl_add_u64 v[184:185], s[4:5], 0, v[48:49]
	s_add_u32 s4, s20, s12
	v_and_b32_e32 v16, 15, v74
	s_addc_u32 s5, s21, s3
	v_mov_b64_e32 v[12:13], s[52:53]
	v_sub_f32_e32 v157, v33, v168
	v_sub_f32_e32 v158, v34, v168
	v_sub_f32_e32 v159, v35, v168
	v_sub_f32_e32 v146, v36, v168
	v_sub_f32_e32 v147, v37, v168
	v_sub_f32_e32 v148, v38, v168
	v_sub_f32_e32 v149, v39, v168
	v_sub_f32_e32 v150, v40, v168
	v_sub_f32_e32 v151, v41, v168
	v_sub_f32_e32 v154, v42, v168
	v_sub_f32_e32 v155, v43, v168
	v_sub_f32_e32 v144, v44, v168
	v_sub_f32_e32 v145, v45, v168
	v_sub_f32_e32 v152, v46, v168
	v_sub_f32_e32 v153, v47, v168
	v_cndmask_b32_e64 v210, v32, 1.0, vcc
	v_lshlrev_b32_e32 v176, 4, v16
	v_lshl_add_u64 v[186:187], s[4:5], 0, v[48:49]
	v_mov_b64_e32 v[62:63], v[14:15]
	v_mov_b64_e32 v[46:47], v[14:15]
	v_mov_b64_e32 v[30:31], v[14:15]
	v_readlane_b32 s52, v254, 62
	v_readlane_b32 s54, v255, 0
	v_cmp_gt_u32_e64 s[6:7], 32, v75
	v_add_u32_e32 v196, s15, v76
	v_mov_b64_e32 v[60:61], v[12:13]
	v_mov_b64_e32 v[58:59], v[10:11]
	v_mov_b64_e32 v[56:57], v[8:9]
	v_mov_b64_e32 v[54:55], v[6:7]
	v_mov_b64_e32 v[52:53], v[4:5]
	v_mov_b64_e32 v[50:51], v[2:3]
	v_mov_b64_e32 v[48:49], v[0:1]
	v_mov_b64_e32 v[44:45], v[12:13]
	v_mov_b64_e32 v[42:43], v[10:11]
	v_mov_b64_e32 v[40:41], v[8:9]
	v_mov_b64_e32 v[38:39], v[6:7]
	v_mov_b64_e32 v[36:37], v[4:5]
	v_mov_b64_e32 v[34:35], v[2:3]
	v_mov_b64_e32 v[32:33], v[0:1]
	v_mov_b64_e32 v[28:29], v[12:13]
	v_mov_b64_e32 v[26:27], v[10:11]
	v_mov_b64_e32 v[24:25], v[8:9]
	v_mov_b64_e32 v[22:23], v[6:7]
	v_mov_b64_e32 v[20:21], v[4:5]
	v_mov_b64_e32 v[18:19], v[2:3]
	v_mov_b64_e32 v[16:17], v[0:1]
	v_readlane_b32 s53, v254, 63
	v_readlane_b32 s55, v255, 1
; #define AB_SBAR() __builtin_amdgcn_sched_barrier(0)
; #define AB_SLOAD(Z, k0) do { sZ##_dummy: ; } while (0)
; #define AB_SLOAD(Z, k0) do { s##Z##_vs0 = *reinterpret_cast<const bf16x8*>(&Vh[(long)((k0) + sr) * LDKV + sc]); s##Z##_vs1 = *reinterpret_cast<const bf16x8*>(&Vh[(long)((k0) + 32 + sr) * LDKV + sc]); \
;     s##Z##_ks0 = *reinterpret_cast<const bf16x8*>(&Kh[(long)((k0) + sr) * LDKV + sc]); s##Z##_ks1 = *reinterpret_cast<const bf16x8*>(&Kh[(long)((k0) + 32 + sr) * LDKV + sc]); } while (0)
; __device__ __forceinline__ void finishSM(f32x16& p0, f32x16& p1, float alpha, float& l_reg, bf16x8& pa0, bf16x8& pa1, bf16x8& pa2, bf16x8& pa3) {
; #pragma unroll
;   for (int r = 0; r < 16; ++r) p1[r] = __builtin_amdgcn_exp2f(p1[r]);
;   float ps = 0;
; #pragma unroll
;   for (int r = 0; r < 16; ++r) ps += p0[r];
; #pragma unroll
;   for (int r = 0; r < 16; ++r) ps += p1[r];
;   { auto rr = __builtin_amdgcn_permlane32_swap(__float_as_uint(ps), __float_as_uint(ps), false, false);
;     ps = __uint_as_float(rr[0]) + __uint_as_float(rr[1]); }
;   l_reg = l_reg * alpha + ps;
;     ...
;   AB_PK4(p0, 0, pa0); AB_PK4(p0, 8, pa1); AB_PK4(p1, 0, pa2); AB_PK4(p1, 8, pa3);
;     ...
; }
; __device__ __forceinline__ void qkt(f32x16& p0, f32x16& p1, const char* Ks, const bf16x8* qr, int r32, int hi) {
;   p0 = f32x16{}; p1 = f32x16{};
; #pragma unroll
;   for (int d0 = 0; d0 < 8; ++d0) { const int cb = (d0 * 16 + hi * 8) * 2;
;     const bf16x8 b0 = *reinterpret_cast<const bf16x8*>(Ks + AB_KSWZ(r32, cb));
;     const bf16x8 b1 = *reinterpret_cast<const bf16x8*>(Ks + AB_KSWZ(32 + r32, cb));
;     p0 = __builtin_amdgcn_mfma_f32_32x32x16_bf16(b0, qr[d0], p0, 0, 0, 0);
;     p1 = __builtin_amdgcn_mfma_f32_32x32x16_bf16(b1, qr[d0], p1, 0, 0, 0); }
; }
; template <bool OUT_BF16>
; __device__ __forceinline__ void attn_body(const bf16_t* __restrict__ Qb, int ldq, const bf16_t* __restrict__ Kh, const bf16_t* __restrict__ Vh, void* __restrict__ Ob, int ldo, int seq, char* lds) {
;     ...
;   for (int j = 1; j + 1 < NT; j += 2) {
;     AB_SBAR(); qkt(pB0, pB1, K_lds + SHM_K, qr, r32, hi);
;     finishSM(pA0, pA1, alA, l_reg, pa0, pa1, pa2, pa3); AB_SBAR();
;     AB_SLOAD(B, (j + 2) * KVBLK); AB_SBAR();
;     pv_d0(o, vb0, pa0, pa1, pa2, pa3); partialSM(pB0, pB1, m_reg, mnB, alB);
.LBB0_270:
	ds_read_b128 v[64:67], v202 offset:49152
	ds_read_b128 v[68:71], v202 offset:57344
	ds_read_b128 v[212:215], v207 offset:49152
	ds_read_b128 v[216:219], v207 offset:57344
	v_add_f32_e32 v160, 0, v161
	v_add_f32_e32 v160, v175, v160
	s_waitcnt lgkmcnt(3)
	v_mfma_f32_32x32x16_bf16 v[80:95], v[64:67], v[124:127], 0
	v_add_f32_e32 v160, v162, v160
	v_add_f32_e32 v160, v188, v160
	v_add_f32_e32 v160, v174, v160
	v_add_f32_e32 v160, v189, v160
	v_add_f32_e32 v160, v163, v160
	v_add_f32_e32 v160, v173, v160
	v_add_f32_e32 v160, v164, v160
	s_waitcnt lgkmcnt(2)
	v_mfma_f32_32x32x16_bf16 v[64:79], v[68:71], v[124:127], 0
	v_add_f32_e32 v160, v171, v160
	v_add_f32_e32 v160, v165, v160
	v_add_f32_e32 v160, v172, v160
	v_exp_f32_e32 v156, v156
	v_add_f32_e32 v160, v166, v160
	v_exp_f32_e32 v157, v157
	v_add_f32_e32 v160, v169, v160
	s_waitcnt lgkmcnt(1)
	v_mfma_f32_32x32x16_bf16 v[80:95], v[212:215], v[120:123], v[80:95]
	v_exp_f32_e32 v158, v158
	v_add_f32_e32 v160, v167, v160
	v_exp_f32_e32 v159, v159
	v_add_f32_e32 v160, v170, v160
	v_exp_f32_e32 v146, v146
	v_add_f32_e32 v160, v156, v160
	v_exp_f32_e32 v147, v147
	s_waitcnt lgkmcnt(0)
	v_mfma_f32_32x32x16_bf16 v[64:79], v[216:219], v[120:123], v[64:79]
	ds_read_b128 v[212:215], v206 offset:49152
	ds_read_b128 v[216:219], v206 offset:57344
	v_add_f32_e32 v160, v157, v160
	v_exp_f32_e32 v148, v148
	v_add_f32_e32 v160, v158, v160
	v_exp_f32_e32 v149, v149
	v_add_f32_e32 v160, v159, v160
	v_exp_f32_e32 v150, v150
	s_waitcnt lgkmcnt(1)
	v_mfma_f32_32x32x16_bf16 v[80:95], v[212:215], v[116:119], v[80:95]
	v_add_f32_e32 v160, v146, v160
	v_exp_f32_e32 v151, v151
	v_add_f32_e32 v160, v147, v160
	v_exp_f32_e32 v154, v154
	v_add_f32_e32 v160, v148, v160
	v_exp_f32_e32 v155, v155
	v_add_f32_e32 v160, v149, v160
	s_waitcnt lgkmcnt(0)
	v_mfma_f32_32x32x16_bf16 v[64:79], v[216:219], v[116:119], v[64:79]
	ds_read_b128 v[212:215], v205 offset:49152
	ds_read_b128 v[216:219], v205 offset:57344
	v_exp_f32_e32 v144, v144
	v_add_f32_e32 v160, v150, v160
	v_exp_f32_e32 v145, v145
	v_add_f32_e32 v160, v151, v160
	v_exp_f32_e32 v152, v152
	v_add_f32_e32 v160, v154, v160
	s_waitcnt lgkmcnt(1)
	v_mfma_f32_32x32x16_bf16 v[80:95], v[212:215], v[112:115], v[80:95]
	v_exp_f32_e32 v153, v153
	v_add_f32_e32 v160, v155, v160
	v_add_f32_e32 v160, v144, v160
	v_add_f32_e32 v160, v145, v160
	v_add_f32_e32 v160, v152, v160
	v_add_f32_e32 v211, v153, v160
	v_cvt_pk_bf16_f32 v160, v161, v175
	s_waitcnt lgkmcnt(0)
	v_mfma_f32_32x32x16_bf16 v[64:79], v[216:219], v[112:115], v[64:79]
	v_cvt_pk_bf16_f32 v161, v162, v188
	v_cvt_pk_bf16_f32 v162, v174, v189
	v_cvt_pk_bf16_f32 v163, v163, v173
	v_cvt_pk_bf16_f32 v164, v164, v171
	v_cvt_pk_bf16_f32 v165, v165, v172
	v_cvt_pk_bf16_f32 v166, v166, v169
	v_permlane32_swap_b32_e32 v160, v162
	v_cvt_pk_bf16_f32 v167, v167, v170
	v_cvt_pk_bf16_f32 v170, v156, v157
	v_cvt_pk_bf16_f32 v171, v158, v159
	v_cvt_pk_bf16_f32 v172, v146, v147
	v_cvt_pk_bf16_f32 v173, v148, v149
	v_permlane32_swap_b32_e32 v161, v163
	v_permlane32_swap_b32_e32 v164, v166
	v_permlane32_swap_b32_e32 v165, v167
	v_permlane32_swap_b32_e32 v170, v172
	v_permlane32_swap_b32_e32 v171, v173
	v_mov_b32_e32 v212, v211
	s_nop 1
	v_permlane32_swap_b32_e32 v211, v212
	v_cvt_pk_bf16_f32 v214, v150, v151
	v_cvt_pk_bf16_f32 v215, v154, v155
	v_cvt_pk_bf16_f32 v216, v144, v145
	v_cvt_pk_bf16_f32 v217, v152, v153
	s_nop 0
	v_permlane32_swap_b32_e32 v214, v216
	v_permlane32_swap_b32_e32 v215, v217
	v_lshl_add_u64 v[190:191], v[184:185], 0, v[176:177]
	s_mov_b32 s3, 0x34d78000
	v_add_co_u32_e32 v144, vcc, s3, v190
	s_mov_b32 s3, 0x34d7a000
	s_nop 0
	v_addc_co_u32_e32 v145, vcc, 0, v191, vcc
	v_add_co_u32_e32 v148, vcc, s3, v190
	v_lshl_add_u64 v[188:189], v[186:187], 0, v[176:177]
	s_nop 0
	v_addc_co_u32_e32 v149, vcc, 0, v191, vcc
	s_mov_b32 s3, 0x33b78000
	v_add_co_u32_e32 v152, vcc, s3, v188
	s_mov_b32 s3, 0x33b7a000
	s_nop 0
	v_addc_co_u32_e32 v153, vcc, 0, v189, vcc
	v_add_co_u32_e32 v156, vcc, s3, v188
	global_load_dwordx4 v[144:147], v[144:145], off
	s_nop 0
	global_load_dwordx4 v[148:151], v[148:149], off
	v_addc_co_u32_e32 v157, vcc, 0, v189, vcc
	global_load_dwordx4 v[152:155], v[152:153], off
	s_nop 0
	global_load_dwordx4 v[156:159], v[156:157], off
	ds_read_b64_tr_b16 v[218:219], v197 offset:0
	ds_read_b64_tr_b16 v[220:221], v197 offset:0x800
	ds_read_b64_tr_b16 v[222:223], v197 offset:0x1000
	ds_read_b64_tr_b16 v[224:225], v197 offset:0x1800
	ds_read_b64_tr_b16 v[246:247], v197 offset:0x2000
	ds_read_b64_tr_b16 v[248:249], v197 offset:0x2800
	ds_read_b64_tr_b16 v[250:251], v197 offset:0x3000
	ds_read_b64_tr_b16 v[252:253], v197 offset:0x3800
	s_waitcnt lgkmcnt(0)
	s_nop 0
	v_mfma_f32_32x32x16_bf16 v[0:15], v[160:163], v[218:221], v[0:15]
	ds_read_b64_tr_b16 v[218:219], v197 offset:0x200
	ds_read_b64_tr_b16 v[220:221], v197 offset:0xa00
	v_mfma_f32_32x32x16_bf16 v[0:15], v[164:167], v[222:225], v[0:15]
	ds_read_b64_tr_b16 v[222:223], v197 offset:0x1200
	ds_read_b64_tr_b16 v[224:225], v197 offset:0x1a00
	v_mfma_f32_32x32x16_bf16 v[0:15], v[170:173], v[246:249], v[0:15]
	ds_read_b64_tr_b16 v[246:247], v197 offset:0x2200
	ds_read_b64_tr_b16 v[248:249], v197 offset:0x2a00
	v_mfma_f32_32x32x16_bf16 v[0:15], v[214:217], v[250:253], v[0:15]
	ds_read_b64_tr_b16 v[250:251], v197 offset:0x3200
	ds_read_b64_tr_b16 v[252:253], v197 offset:0x3a00
	s_waitcnt lgkmcnt(0)
; #define AB_SBAR() __builtin_amdgcn_sched_barrier(0)
; #define AB_SWRITE(b, Z) do { *(bf16x8*)(V_lds + (b) * SHM_V + vst0) = s##Z##_vs0; *(bf16x8*)(V_lds + (b) * SHM_V + vst1) = s##Z##_vs1; const int kc = sc * 2;               \
;     *(bf16x8*)(K_lds + (b) * SHM_K + AB_KSWZ(sr, kc)) = s##Z##_ks0; *(bf16x8*)(K_lds + (b) * SHM_K + AB_KSWZ(32 + sr, kc)) = s##Z##_ks1; } while (0)
; #define AB_SWAIT() asm volatile("s_waitcnt vmcnt(4)" ::: "memory")
; #define AB_RESC(a) do { if (__any((a) < 1.f)) { if (hi == 0) al_l[r32] = (a); asm volatile("s_waitcnt lgkmcnt(0)" ::: "memory"); \
;     _Pragma("unroll") for (int d = 0; d < 4; ++d) _Pragma("unroll") for (int r = 0; r < 16; ++r) o[d][r] *= al_l[crow(r, hi)]; } } while (0)
; template <int D0> __device__ __forceinline__ void pv_one(f32x16& od, int vb, bf16x8 pa0, bf16x8 pa1, bf16x8 pa2, bf16x8 pa3) {
;   const s16x4 l0 = tr_read<v_rd_off(D0, 0, 0)>(vb), h0 = tr_read<v_rd_off(D0, 0, 1)>(vb), l1 = tr_read<v_rd_off(D0, 1, 0)>(vb), h1 = tr_read<v_rd_off(D0, 1, 1)>(vb);
;   const s16x4 l2 = tr_read<v_rd_off(D0, 2, 0)>(vb), h2 = tr_read<v_rd_off(D0, 2, 1)>(vb), l3 = tr_read<v_rd_off(D0, 3, 0)>(vb), h3 = tr_read<v_rd_off(D0, 3, 1)>(vb);
;   asm volatile("s_waitcnt lgkmcnt(0)" ::: "memory"); AB_SBAR();
;     ...
;   od = __builtin_amdgcn_mfma_f32_32x32x16_bf16(pa0, AB_PK(l0, h0), od, 0, 0, 0);
;   od = __builtin_amdgcn_mfma_f32_32x32x16_bf16(pa1, AB_PK(l1, h1), od, 0, 0, 0);
;   od = __builtin_amdgcn_mfma_f32_32x32x16_bf16(pa2, AB_PK(l2, h2), od, 0, 0, 0);
;   od = __builtin_amdgcn_mfma_f32_32x32x16_bf16(pa3, AB_PK(l3, h3), od, 0, 0, 0);
;     ...
; }
; __device__ __forceinline__ void pv_d0(f32x16* o, int vb, bf16x8 pa0, bf16x8 pa1, bf16x8 pa2, bf16x8 pa3) {
;   pv_one<0>(o[0], vb, pa0, pa1, pa2, pa3); pv_one<1>(o[1], vb, pa0, pa1, pa2, pa3); pv_one<2>(o[2], vb, pa0, pa1, pa2, pa3); pv_one<3>(o[3], vb, pa0, pa1, pa2, pa3);
; template <bool OUT_BF16>
; __device__ __forceinline__ void attn_body(const bf16_t* __restrict__ Qb, int ldq, const bf16_t* __restrict__ Kh, const bf16_t* __restrict__ Vh, void* __restrict__ Ob, int ldo, int seq, char* lds) {
;     ...
;     pv_d0(o, vb0, pa0, pa1, pa2, pa3); partialSM(pB0, pB1, m_reg, mnB, alB);
;     __syncthreads(); AB_SWAIT(); AB_SWRITE(0, A);
;     AB_RESC(alB); __syncthreads();
	v_mfma_f32_32x32x16_bf16 v[48:63], v[160:163], v[218:221], v[48:63]
	ds_read_b64_tr_b16 v[218:219], v197 offset:0x400
	ds_read_b64_tr_b16 v[220:221], v197 offset:0xc00
	v_mfma_f32_32x32x16_bf16 v[48:63], v[164:167], v[222:225], v[48:63]
	ds_read_b64_tr_b16 v[222:223], v197 offset:0x1400
	ds_read_b64_tr_b16 v[224:225], v197 offset:0x1c00
	v_mfma_f32_32x32x16_bf16 v[48:63], v[170:173], v[246:249], v[48:63]
	ds_read_b64_tr_b16 v[246:247], v197 offset:0x2400
	ds_read_b64_tr_b16 v[248:249], v197 offset:0x2c00
	v_mfma_f32_32x32x16_bf16 v[48:63], v[214:217], v[250:253], v[48:63]
	ds_read_b64_tr_b16 v[250:251], v197 offset:0x3400
	ds_read_b64_tr_b16 v[252:253], v197 offset:0x3c00
	s_waitcnt lgkmcnt(0)
	v_mfma_f32_32x32x16_bf16 v[32:47], v[160:163], v[218:221], v[32:47]
	ds_read_b64_tr_b16 v[218:219], v197 offset:0x600
	ds_read_b64_tr_b16 v[220:221], v197 offset:0xe00
	v_mfma_f32_32x32x16_bf16 v[32:47], v[164:167], v[222:225], v[32:47]
	ds_read_b64_tr_b16 v[222:223], v197 offset:0x1600
	ds_read_b64_tr_b16 v[224:225], v197 offset:0x1e00
	v_mfma_f32_32x32x16_bf16 v[32:47], v[170:173], v[246:249], v[32:47]
	ds_read_b64_tr_b16 v[246:247], v197 offset:0x2600
	ds_read_b64_tr_b16 v[248:249], v197 offset:0x2e00
	v_mfma_f32_32x32x16_bf16 v[32:47], v[214:217], v[250:253], v[32:47]
	ds_read_b64_tr_b16 v[250:251], v197 offset:0x3600
	ds_read_b64_tr_b16 v[252:253], v197 offset:0x3e00
	s_waitcnt lgkmcnt(0)
	v_mfma_f32_32x32x16_bf16 v[16:31], v[160:163], v[218:221], v[16:31]
	v_max_f32_e32 v160, v81, v81
	v_max_f32_e32 v161, v80, v80
	v_max_f32_e32 v160, v161, v160
	v_max3_f32 v160, v160, v82, v83
	v_max3_f32 v160, v160, v84, v85
	v_max3_f32 v160, v160, v86, v87
	v_max3_f32 v160, v160, v88, v89
	v_max3_f32 v160, v160, v90, v91
	v_mfma_f32_32x32x16_bf16 v[16:31], v[164:167], v[222:225], v[16:31]
	v_max3_f32 v160, v160, v92, v93
	v_max3_f32 v160, v160, v94, v95
	v_max3_f32 v160, v160, v64, v65
	v_max3_f32 v160, v160, v66, v67
	v_max3_f32 v160, v160, v68, v69
	v_max3_f32 v160, v160, v70, v71
	v_max3_f32 v160, v160, v72, v73
	v_max3_f32 v160, v160, v74, v75
	v_mfma_f32_32x32x16_bf16 v[16:31], v[170:173], v[246:249], v[16:31]
	v_max3_f32 v160, v160, v76, v77
	v_max3_f32 v160, v160, v78, v79
	v_mov_b32_e32 v161, v160
	s_nop 1
	v_permlane32_swap_b32_e32 v160, v161
	v_max_f32_e32 v161, v161, v161
	v_max_f32_e32 v160, v160, v160
	v_max_f32_e32 v160, v160, v161
	v_sub_f32_e32 v161, v160, v168
	v_cmp_ge_f32_e32 vcc, s22, v161
	v_max_f32_e32 v161, v168, v168
	v_mfma_f32_32x32x16_bf16 v[16:31], v[214:217], v[250:253], v[16:31]
	v_max_f32_e32 v160, v161, v160
	v_sub_f32_e32 v161, v168, v160
	v_exp_f32_e32 v161, v161
	s_cmp_eq_u64 vcc, exec
	s_cselect_b64 s[4:5], -1, 0
	s_barrier
	s_waitcnt vmcnt(4)
	v_cndmask_b32_e64 v213, v161, 1.0, s[4:5]
	v_cmp_gt_f32_e32 vcc, 1.0, v213
	s_waitcnt vmcnt(4)
	ds_write_b128 v199, v[128:131]
	ds_write_b128 v200, v[132:135]
	ds_write_b128 v198, v[136:139] offset:32768
	ds_write_b128 v201, v[140:143] offset:32768
	s_cbranch_vccz .LBB0_274
	s_and_saveexec_b64 s[12:13], s[6:7]
	ds_write_b32 v194, v213 offset:128
	s_or_b64 exec, exec, s[12:13]
	s_waitcnt lgkmcnt(0)
	v_add_u32_e32 v161, v193, v182
	ds_read_b128 v[162:165], v161 offset:224
	ds_read_b128 v[170:173], v161 offset:192
	ds_read_b128 v[214:217], v161 offset:160
	ds_read_b128 v[218:221], v161 offset:128
	s_waitcnt lgkmcnt(3)
	v_pk_mul_f32 v[12:13], v[12:13], v[162:163]
	s_waitcnt lgkmcnt(2)
	v_pk_mul_f32 v[8:9], v[8:9], v[170:171]
	s_waitcnt lgkmcnt(1)
	v_pk_mul_f32 v[4:5], v[4:5], v[214:215]
	v_pk_mul_f32 v[14:15], v[14:15], v[164:165]
	v_pk_mul_f32 v[10:11], v[10:11], v[172:173]
	v_pk_mul_f32 v[6:7], v[6:7], v[216:217]
	s_waitcnt lgkmcnt(0)
	v_pk_mul_f32 v[2:3], v[2:3], v[220:221]
	v_pk_mul_f32 v[0:1], v[0:1], v[218:219]
	v_pk_mul_f32 v[60:61], v[60:61], v[162:163]
	v_pk_mul_f32 v[56:57], v[56:57], v[170:171]
	v_pk_mul_f32 v[52:53], v[52:53], v[214:215]
	v_pk_mul_f32 v[62:63], v[62:63], v[164:165]
	v_pk_mul_f32 v[58:59], v[58:59], v[172:173]
	v_pk_mul_f32 v[54:55], v[54:55], v[216:217]
	v_pk_mul_f32 v[50:51], v[50:51], v[220:221]
	v_pk_mul_f32 v[48:49], v[48:49], v[218:219]
	v_pk_mul_f32 v[44:45], v[44:45], v[162:163]
	v_pk_mul_f32 v[40:41], v[40:41], v[170:171]
	v_pk_mul_f32 v[36:37], v[36:37], v[214:215]
	v_pk_mul_f32 v[46:47], v[46:47], v[164:165]
	v_pk_mul_f32 v[42:43], v[42:43], v[172:173]
	v_pk_mul_f32 v[38:39], v[38:39], v[216:217]
	v_pk_mul_f32 v[34:35], v[34:35], v[220:221]
	v_pk_mul_f32 v[32:33], v[32:33], v[218:219]
	v_pk_mul_f32 v[28:29], v[28:29], v[162:163]
	v_pk_mul_f32 v[24:25], v[24:25], v[170:171]
	v_pk_mul_f32 v[20:21], v[20:21], v[214:215]
	v_pk_mul_f32 v[30:31], v[30:31], v[164:165]
	v_pk_mul_f32 v[26:27], v[26:27], v[172:173]
	v_pk_mul_f32 v[22:23], v[22:23], v[216:217]
	v_pk_mul_f32 v[18:19], v[18:19], v[220:221]
	v_pk_mul_f32 v[16:17], v[16:17], v[218:219]
; #define AB_SBAR() __builtin_amdgcn_sched_barrier(0)
; #define AB_SLOAD(Z, k0) do { sZ##_dummy: ; } while (0)
; __device__ __forceinline__ void partialSM(f32x16& p0, f32x16& p1, float& m_reg, float& mn, float& alpha) {
;     ...
;   for (int r = 0; r < 16; ++r) p0[r] = p0[r] - mn;
; #pragma unroll
;   for (int r = 0; r < 16; ++r) p1[r] = p1[r] - mn;
; #pragma unroll
;   for (int r = 0; r < 16; ++r) p0[r] = __builtin_amdgcn_exp2f(p0[r]);
; }
; __device__ __forceinline__ void finishSM(f32x16& p0, f32x16& p1, float alpha, float& l_reg, bf16x8& pa0, bf16x8& pa1, bf16x8& pa2, bf16x8& pa3) {
; #pragma unroll
;   for (int r = 0; r < 16; ++r) p1[r] = __builtin_amdgcn_exp2f(p1[r]);
;   float ps = 0;
; #pragma unroll
;   for (int r = 0; r < 16; ++r) ps += p0[r];
; #pragma unroll
;   for (int r = 0; r < 16; ++r) ps += p1[r];
;   { auto rr = __builtin_amdgcn_permlane32_swap(__float_as_uint(ps), __float_as_uint(ps), false, false);
;     ps = __uint_as_float(rr[0]) + __uint_as_float(rr[1]); }
;   l_reg = l_reg * alpha + ps;
;     ...
;   AB_PK4(p0, 0, pa0); AB_PK4(p0, 8, pa1); AB_PK4(p1, 0, pa2); AB_PK4(p1, 8, pa3);
;     ...
; }
; __device__ __forceinline__ void qkt(f32x16& p0, f32x16& p1, const char* Ks, const bf16x8* qr, int r32, int hi) {
;   p0 = f32x16{}; p1 = f32x16{};
; #pragma unroll
;   for (int d0 = 0; d0 < 8; ++d0) { const int cb = (d0 * 16 + hi * 8) * 2;
;     const bf16x8 b0 = *reinterpret_cast<const bf16x8*>(Ks + AB_KSWZ(r32, cb));
;     const bf16x8 b1 = *reinterpret_cast<const bf16x8*>(Ks + AB_KSWZ(32 + r32, cb));
;     p0 = __builtin_amdgcn_mfma_f32_32x32x16_bf16(b0, qr[d0], p0, 0, 0, 0);
;     p1 = __builtin_amdgcn_mfma_f32_32x32x16_bf16(b1, qr[d0], p1, 0, 0, 0); }
; }
; template <bool OUT_BF16>
; __device__ __forceinline__ void attn_body(const bf16_t* __restrict__ Qb, int ldq, const bf16_t* __restrict__ Kh, const bf16_t* __restrict__ Vh, void* __restrict__ Ob, int ldo, int seq, char* lds) {
;     ...
;     AB_SBAR(); qkt(pA0, pA1, K_lds, qr, r32, hi);
;     finishSM(pB0, pB1, alB, l_reg, pa0, pa1, pa2, pa3); AB_SBAR();
;     if (j + 3 < NT) AB_SLOAD(A, (j + 3) * KVBLK); AB_SBAR();
.LBB0_274:
	v_cndmask_b32_e64 v214, v160, v168, s[4:5]
	v_sub_f32_e32 v80, v80, v214
	v_sub_f32_e32 v81, v81, v214
	v_sub_f32_e32 v82, v82, v214
	v_sub_f32_e32 v83, v83, v214
	v_sub_f32_e32 v84, v84, v214
	v_sub_f32_e32 v85, v85, v214
	v_sub_f32_e32 v86, v86, v214
	v_sub_f32_e32 v87, v87, v214
	v_sub_f32_e32 v88, v88, v214
	v_sub_f32_e32 v89, v89, v214
	v_sub_f32_e32 v90, v90, v214
	v_sub_f32_e32 v91, v91, v214
	v_sub_f32_e32 v92, v92, v214
	v_sub_f32_e32 v93, v93, v214
	v_sub_f32_e32 v94, v94, v214
	v_sub_f32_e32 v95, v95, v214
	v_exp_f32_e32 v160, v80
	v_exp_f32_e32 v175, v81
	v_exp_f32_e32 v161, v82
	v_exp_f32_e32 v174, v83
	v_exp_f32_e32 v162, v84
	v_exp_f32_e32 v173, v85
	v_exp_f32_e32 v163, v86
	v_exp_f32_e32 v172, v87
	v_exp_f32_e32 v164, v88
	v_exp_f32_e32 v171, v89
	v_exp_f32_e32 v165, v90
	v_exp_f32_e32 v170, v91
	v_exp_f32_e32 v166, v92
	v_exp_f32_e32 v169, v93
	v_exp_f32_e32 v167, v94
	v_exp_f32_e32 v168, v95
	v_sub_f32_e32 v215, v64, v214
	v_sub_f32_e32 v224, v65, v214
	v_sub_f32_e32 v225, v66, v214
	v_sub_f32_e32 v226, v67, v214
	v_sub_f32_e32 v227, v68, v214
	v_sub_f32_e32 v245, v69, v214
	v_sub_f32_e32 v246, v70, v214
	v_sub_f32_e32 v247, v71, v214
	v_sub_f32_e32 v248, v72, v214
	v_sub_f32_e32 v249, v73, v214
	v_sub_f32_e32 v250, v74, v214
	v_sub_f32_e32 v251, v75, v214
	v_sub_f32_e32 v252, v76, v214
	v_sub_f32_e32 v253, v77, v214
	v_sub_f32_e32 v238, v78, v214
	v_sub_f32_e32 v239, v79, v214
	s_waitcnt lgkmcnt(0)
	s_barrier
	ds_read_b128 v[64:67], v202 offset:32768
	ds_read_b128 v[68:71], v202 offset:40960
	ds_read_b128 v[216:219], v207 offset:32768
	ds_read_b128 v[220:223], v207 offset:40960
	v_exp_f32_e32 v238, v238
	v_exp_f32_e32 v239, v239
	s_waitcnt lgkmcnt(3)
	v_mfma_f32_32x32x16_bf16 v[80:95], v[64:67], v[124:127], 0
	s_waitcnt lgkmcnt(2)
	v_mfma_f32_32x32x16_bf16 v[64:79], v[68:71], v[124:127], 0
	s_waitcnt lgkmcnt(1)
	v_mfma_f32_32x32x16_bf16 v[80:95], v[216:219], v[120:123], v[80:95]
	s_waitcnt lgkmcnt(0)
	v_mfma_f32_32x32x16_bf16 v[64:79], v[220:223], v[120:123], v[64:79]
	ds_read_b128 v[216:219], v206 offset:32768
	ds_read_b128 v[220:223], v206 offset:40960
	s_waitcnt lgkmcnt(1)
	v_mfma_f32_32x32x16_bf16 v[80:95], v[216:219], v[116:119], v[80:95]
	s_waitcnt lgkmcnt(0)
	v_mfma_f32_32x32x16_bf16 v[64:79], v[220:223], v[116:119], v[64:79]
	ds_read_b128 v[216:219], v205 offset:32768
	ds_read_b128 v[220:223], v205 offset:40960
	s_waitcnt lgkmcnt(1)
	v_mfma_f32_32x32x16_bf16 v[80:95], v[216:219], v[112:115], v[80:95]
	s_waitcnt lgkmcnt(0)
	v_mfma_f32_32x32x16_bf16 v[64:79], v[220:223], v[112:115], v[64:79]
	v_exp_f32_e32 v217, v215
	v_add_f32_e32 v215, 0, v160
	v_add_f32_e32 v215, v175, v215
	v_add_f32_e32 v215, v161, v215
	v_add_f32_e32 v215, v174, v215
	v_add_f32_e32 v215, v162, v215
	v_add_f32_e32 v215, v173, v215
	v_add_f32_e32 v215, v163, v215
	v_add_f32_e32 v215, v172, v215
	v_add_f32_e32 v215, v164, v215
	v_add_f32_e32 v215, v171, v215
	v_add_f32_e32 v215, v165, v215
	v_add_f32_e32 v215, v170, v215
	v_add_f32_e32 v215, v166, v215
	v_exp_f32_e32 v218, v224
	v_add_f32_e32 v215, v169, v215
	v_exp_f32_e32 v219, v225
	v_add_f32_e32 v215, v167, v215
	v_exp_f32_e32 v220, v226
	v_add_f32_e32 v215, v168, v215
	v_exp_f32_e32 v221, v227
	v_add_f32_e32 v215, v217, v215
	v_exp_f32_e32 v222, v245
	v_add_f32_e32 v215, v218, v215
	v_exp_f32_e32 v223, v246
	v_add_f32_e32 v215, v219, v215
	v_exp_f32_e32 v224, v247
	v_add_f32_e32 v215, v220, v215
	v_exp_f32_e32 v225, v248
	v_add_f32_e32 v215, v221, v215
	v_exp_f32_e32 v226, v249
	v_add_f32_e32 v215, v222, v215
	v_exp_f32_e32 v227, v250
	v_add_f32_e32 v215, v223, v215
	v_exp_f32_e32 v245, v251
	v_add_f32_e32 v215, v224, v215
	v_exp_f32_e32 v246, v252
	v_add_f32_e32 v215, v225, v215
	v_exp_f32_e32 v247, v253
	v_add_f32_e32 v215, v226, v215
	v_add_f32_e32 v215, v227, v215
	v_add_f32_e32 v215, v245, v215
	v_add_f32_e32 v215, v246, v215
	v_add_f32_e32 v215, v247, v215
	v_add_f32_e32 v215, v238, v215
	v_add_f32_e32 v215, v239, v215
	v_mov_b32_e32 v216, v215
	v_cvt_pk_bf16_f32 v160, v160, v175
	v_cvt_pk_bf16_f32 v161, v161, v174
	v_cvt_pk_bf16_f32 v162, v162, v173
	v_cvt_pk_bf16_f32 v163, v163, v172
	v_cvt_pk_bf16_f32 v164, v164, v171
	v_cvt_pk_bf16_f32 v165, v165, v170
	v_cvt_pk_bf16_f32 v166, v166, v169
	v_cvt_pk_bf16_f32 v167, v167, v168
	v_cvt_pk_bf16_f32 v168, v217, v218
	v_cvt_pk_bf16_f32 v169, v219, v220
	v_cvt_pk_bf16_f32 v170, v221, v222
	v_cvt_pk_bf16_f32 v171, v223, v224
	v_cvt_pk_bf16_f32 v172, v225, v226
	v_cvt_pk_bf16_f32 v173, v227, v245
	v_cvt_pk_bf16_f32 v174, v246, v247
	v_cvt_pk_bf16_f32 v175, v238, v239
	s_nop 1
	v_permlane32_swap_b32_e32 v215, v216
	v_permlane32_swap_b32_e32 v160, v162
	v_permlane32_swap_b32_e32 v161, v163
	v_permlane32_swap_b32_e32 v164, v166
	v_permlane32_swap_b32_e32 v165, v167
	v_permlane32_swap_b32_e32 v168, v170
	v_permlane32_swap_b32_e32 v169, v171
	v_permlane32_swap_b32_e32 v172, v174
	v_permlane32_swap_b32_e32 v173, v175
	s_cmp_ge_u32 s18, s19
	s_cselect_b64 s[12:13], -1, 0
	s_and_b64 vcc, exec, s[12:13]
	s_cbranch_vccnz .LBB0_276
	v_add_co_u32_e32 v128, vcc, 0x34d7c000, v190
	s_nop 1
	v_addc_co_u32_e32 v129, vcc, 0, v191, vcc
	v_add_co_u32_e32 v132, vcc, 0x34d7e000, v190
	s_nop 1
	v_addc_co_u32_e32 v133, vcc, 0, v191, vcc
	v_add_co_u32_e32 v136, vcc, 0x33b7c000, v188
	global_load_dwordx4 v[128:131], v[128:129], off
	s_nop 0
	global_load_dwordx4 v[132:135], v[132:133], off
	v_addc_co_u32_e32 v137, vcc, 0, v189, vcc
	v_add_co_u32_e32 v140, vcc, 0x33b7e000, v188
	s_nop 1
	v_addc_co_u32_e32 v141, vcc, 0, v189, vcc
	global_load_dwordx4 v[136:139], v[136:137], off
	s_nop 0
	global_load_dwordx4 v[140:143], v[140:141], off

; #define AB_SBAR() __builtin_amdgcn_sched_barrier(0)
; __device__ __forceinline__ void finishSM(f32x16& p0, f32x16& p1, float alpha, float& l_reg, bf16x8& pa0, bf16x8& pa1, bf16x8& pa2, bf16x8& pa3) {
; #pragma unroll
;   for (int r = 0; r < 16; ++r) p1[r] = __builtin_amdgcn_exp2f(p1[r]);
;   float ps = 0;
; #pragma unroll
;   for (int r = 0; r < 16; ++r) ps += p0[r];
; #pragma unroll
;   for (int r = 0; r < 16; ++r) ps += p1[r];
;   { auto rr = __builtin_amdgcn_permlane32_swap(__float_as_uint(ps), __float_as_uint(ps), false, false);
;     ps = __uint_as_float(rr[0]) + __uint_as_float(rr[1]); }
;   l_reg = l_reg * alpha + ps;
;     ...
;   AB_PK4(p0, 0, pa0); AB_PK4(p0, 8, pa1); AB_PK4(p1, 0, pa2); AB_PK4(p1, 8, pa3);
;     ...
; }
; __device__ __forceinline__ void qkt(f32x16& p0, f32x16& p1, const char* Ks, const bf16x8* qr, int r32, int hi) {
;   p0 = f32x16{}; p1 = f32x16{};
; #pragma unroll
;   for (int d0 = 0; d0 < 8; ++d0) { const int cb = (d0 * 16 + hi * 8) * 2;
;     const bf16x8 b0 = *reinterpret_cast<const bf16x8*>(Ks + AB_KSWZ(r32, cb));
;     const bf16x8 b1 = *reinterpret_cast<const bf16x8*>(Ks + AB_KSWZ(32 + r32, cb));
;     p0 = __builtin_amdgcn_mfma_f32_32x32x16_bf16(b0, qr[d0], p0, 0, 0, 0);
;     p1 = __builtin_amdgcn_mfma_f32_32x32x16_bf16(b1, qr[d0], p1, 0, 0, 0); }
; }
; template <bool OUT_BF16>
; __device__ __forceinline__ void attn_body(const bf16_t* __restrict__ Qb, int ldq, const bf16_t* __restrict__ Kh, const bf16_t* __restrict__ Vh, void* __restrict__ Ob, int ldo, int seq, char* lds) {
;     ...
;   AB_SBAR(); qkt(pB0, pB1, K_lds + SHM_K, qr, r32, hi);
;   finishSM(pA0, pA1, alA, l_reg, pa0, pa1, pa2, pa3); AB_SBAR();
;   pv_d0(o, vb0, pa0, pa1, pa2, pa3); partialSM(pB0, pB1, m_reg, mnB, alB);
.LBB0_282:
	ds_read_b128 v[64:67], v202 offset:49152
	ds_read_b128 v[68:71], v202 offset:57344
	s_waitcnt lgkmcnt(1)
	v_mfma_f32_32x32x16_bf16 v[80:95], v[64:67], v[124:127], 0
	s_waitcnt lgkmcnt(0)
	v_mfma_f32_32x32x16_bf16 v[64:79], v[68:71], v[124:127], 0
	ds_read_b128 v[124:127], v207 offset:49152
	ds_read_b128 v[128:131], v207 offset:57344
	s_waitcnt lgkmcnt(1)
	v_mfma_f32_32x32x16_bf16 v[80:95], v[124:127], v[120:123], v[80:95]
	s_waitcnt lgkmcnt(0)
	v_mfma_f32_32x32x16_bf16 v[64:79], v[128:131], v[120:123], v[64:79]
	ds_read_b128 v[120:123], v206 offset:49152
	ds_read_b128 v[124:127], v206 offset:57344
	s_waitcnt lgkmcnt(1)
	v_mfma_f32_32x32x16_bf16 v[80:95], v[120:123], v[116:119], v[80:95]
	s_waitcnt lgkmcnt(0)
	v_mfma_f32_32x32x16_bf16 v[64:79], v[124:127], v[116:119], v[64:79]
	ds_read_b128 v[116:119], v205 offset:49152
	ds_read_b128 v[120:123], v205 offset:57344
	s_waitcnt lgkmcnt(1)
	v_mfma_f32_32x32x16_bf16 v[80:95], v[116:119], v[112:115], v[80:95]
	s_waitcnt lgkmcnt(0)
	v_mfma_f32_32x32x16_bf16 v[64:79], v[120:123], v[112:115], v[64:79]
	v_exp_f32_e32 v120, v152
	v_exp_f32_e32 v121, v153
	v_exp_f32_e32 v116, v154
	v_exp_f32_e32 v117, v155
	v_exp_f32_e32 v118, v144
	v_exp_f32_e32 v119, v145
	v_exp_f32_e32 v112, v148
	v_exp_f32_e32 v113, v149
	v_exp_f32_e32 v114, v150
	v_exp_f32_e32 v115, v151
	v_exp_f32_e32 v108, v158
	v_exp_f32_e32 v109, v159
	v_exp_f32_e32 v110, v146
	v_exp_f32_e32 v111, v147
	v_cvt_pk_bf16_f32 v100, v174, v189
	v_cvt_pk_bf16_f32 v101, v163, v173
	v_cvt_pk_bf16_f32 v102, v164, v171
	v_cvt_pk_bf16_f32 v103, v165, v172
	v_add_f32_e32 v96, 0, v161
	v_add_f32_e32 v96, v175, v96
	v_add_f32_e32 v96, v162, v96
	v_add_f32_e32 v96, v188, v96
	v_add_f32_e32 v96, v174, v96
	v_add_f32_e32 v96, v189, v96
	v_add_f32_e32 v96, v163, v96
	v_add_f32_e32 v96, v173, v96
	v_add_f32_e32 v96, v164, v96
	v_add_f32_e32 v96, v171, v96
	v_add_f32_e32 v96, v165, v96
	v_add_f32_e32 v96, v172, v96
	v_exp_f32_e32 v106, v156
	v_add_f32_e32 v96, v166, v96
	v_exp_f32_e32 v107, v157
	v_add_f32_e32 v96, v169, v96
	v_add_f32_e32 v96, v167, v96
	v_add_f32_e32 v96, v170, v96
	v_add_f32_e32 v96, v106, v96
	v_add_f32_e32 v96, v107, v96
	v_add_f32_e32 v96, v108, v96
	v_add_f32_e32 v96, v109, v96
	v_add_f32_e32 v96, v110, v96
	v_add_f32_e32 v96, v111, v96
	v_add_f32_e32 v96, v112, v96
	v_add_f32_e32 v96, v113, v96
	v_add_f32_e32 v96, v114, v96
	v_add_f32_e32 v96, v115, v96
	v_add_f32_e32 v96, v116, v96
	v_add_f32_e32 v96, v117, v96
	v_add_f32_e32 v96, v118, v96
	v_add_f32_e32 v96, v119, v96
	v_add_f32_e32 v96, v120, v96
	v_add_f32_e32 v96, v121, v96
	v_mov_b32_e32 v97, v96
	v_cvt_pk_bf16_f32 v98, v161, v175
	v_cvt_pk_bf16_f32 v99, v162, v188
	s_nop 1
	v_permlane32_swap_b32_e32 v96, v97
	v_permlane32_swap_b32_e32 v98, v100
	v_permlane32_swap_b32_e32 v99, v101
	v_cvt_pk_bf16_f32 v104, v166, v169
	v_cvt_pk_bf16_f32 v105, v167, v170
	v_cvt_pk_bf16_f32 v106, v106, v107
	v_cvt_pk_bf16_f32 v107, v108, v109
	v_cvt_pk_bf16_f32 v108, v110, v111
	v_cvt_pk_bf16_f32 v109, v112, v113
	v_cvt_pk_bf16_f32 v110, v114, v115
	v_cvt_pk_bf16_f32 v111, v116, v117
	v_cvt_pk_bf16_f32 v112, v118, v119
	v_cvt_pk_bf16_f32 v113, v120, v121
	s_nop 0
	v_permlane32_swap_b32_e32 v102, v104
	v_permlane32_swap_b32_e32 v103, v105
	v_permlane32_swap_b32_e32 v106, v108
	v_permlane32_swap_b32_e32 v107, v109
	v_permlane32_swap_b32_e32 v110, v112
	v_permlane32_swap_b32_e32 v111, v113
	ds_read_b64_tr_b16 v[114:115], v197 offset:0
	ds_read_b64_tr_b16 v[116:117], v197 offset:0x800
	ds_read_b64_tr_b16 v[118:119], v197 offset:0x1000
	ds_read_b64_tr_b16 v[120:121], v197 offset:0x1800
	ds_read_b64_tr_b16 v[122:123], v197 offset:0x2000
	ds_read_b64_tr_b16 v[124:125], v197 offset:0x2800
	ds_read_b64_tr_b16 v[126:127], v197 offset:0x3000
	ds_read_b64_tr_b16 v[128:129], v197 offset:0x3800
	s_waitcnt lgkmcnt(0)
	s_nop 0
	v_mfma_f32_32x32x16_bf16 v[0:15], v[98:101], v[114:117], v[0:15]
	ds_read_b64_tr_b16 v[114:115], v197 offset:0x200
	ds_read_b64_tr_b16 v[116:117], v197 offset:0xa00
	v_mfma_f32_32x32x16_bf16 v[0:15], v[102:105], v[118:121], v[0:15]
	ds_read_b64_tr_b16 v[118:119], v197 offset:0x1200
	ds_read_b64_tr_b16 v[120:121], v197 offset:0x1a00
	v_mfma_f32_32x32x16_bf16 v[0:15], v[106:109], v[122:125], v[0:15]
	ds_read_b64_tr_b16 v[122:123], v197 offset:0x2200
	ds_read_b64_tr_b16 v[124:125], v197 offset:0x2a00
	v_mfma_f32_32x32x16_bf16 v[0:15], v[110:113], v[126:129], v[0:15]
	ds_read_b64_tr_b16 v[126:127], v197 offset:0x3200
	ds_read_b64_tr_b16 v[128:129], v197 offset:0x3a00
	s_waitcnt lgkmcnt(0)
; #define AB_SBAR() __builtin_amdgcn_sched_barrier(0)
; #define AB_RESC(a) do { if (__any((a) < 1.f)) { if (hi == 0) al_l[r32] = (a); asm volatile("s_waitcnt lgkmcnt(0)" ::: "memory"); \
;     _Pragma("unroll") for (int d = 0; d < 4; ++d) _Pragma("unroll") for (int r = 0; r < 16; ++r) o[d][r] *= al_l[crow(r, hi)]; } } while (0)
; template <int D0> __device__ __forceinline__ void pv_one(f32x16& od, int vb, bf16x8 pa0, bf16x8 pa1, bf16x8 pa2, bf16x8 pa3) {
;   const s16x4 l0 = tr_read<v_rd_off(D0, 0, 0)>(vb), h0 = tr_read<v_rd_off(D0, 0, 1)>(vb), l1 = tr_read<v_rd_off(D0, 1, 0)>(vb), h1 = tr_read<v_rd_off(D0, 1, 1)>(vb);
;   const s16x4 l2 = tr_read<v_rd_off(D0, 2, 0)>(vb), h2 = tr_read<v_rd_off(D0, 2, 1)>(vb), l3 = tr_read<v_rd_off(D0, 3, 0)>(vb), h3 = tr_read<v_rd_off(D0, 3, 1)>(vb);
;   asm volatile("s_waitcnt lgkmcnt(0)" ::: "memory"); AB_SBAR();
;     ...
;   od = __builtin_amdgcn_mfma_f32_32x32x16_bf16(pa0, AB_PK(l0, h0), od, 0, 0, 0);
;   od = __builtin_amdgcn_mfma_f32_32x32x16_bf16(pa1, AB_PK(l1, h1), od, 0, 0, 0);
;   od = __builtin_amdgcn_mfma_f32_32x32x16_bf16(pa2, AB_PK(l2, h2), od, 0, 0, 0);
;   od = __builtin_amdgcn_mfma_f32_32x32x16_bf16(pa3, AB_PK(l3, h3), od, 0, 0, 0);
;     ...
; }
; __device__ __forceinline__ void pv_d0(f32x16* o, int vb, bf16x8 pa0, bf16x8 pa1, bf16x8 pa2, bf16x8 pa3) {
;   pv_one<0>(o[0], vb, pa0, pa1, pa2, pa3); pv_one<1>(o[1], vb, pa0, pa1, pa2, pa3); pv_one<2>(o[2], vb, pa0, pa1, pa2, pa3); pv_one<3>(o[3], vb, pa0, pa1, pa2, pa3);
; template <bool OUT_BF16>
; __device__ __forceinline__ void attn_body(const bf16_t* __restrict__ Qb, int ldq, const bf16_t* __restrict__ Kh, const bf16_t* __restrict__ Vh, void* __restrict__ Ob, int ldo, int seq, char* lds) {
;     ...
;   pv_d0(o, vb0, pa0, pa1, pa2, pa3); partialSM(pB0, pB1, m_reg, mnB, alB);
;   __syncthreads(); AB_RESC(alB);
	v_mfma_f32_32x32x16_bf16 v[48:63], v[98:101], v[114:117], v[48:63]
	ds_read_b64_tr_b16 v[114:115], v197 offset:0x400
	ds_read_b64_tr_b16 v[116:117], v197 offset:0xc00
	v_mfma_f32_32x32x16_bf16 v[48:63], v[102:105], v[118:121], v[48:63]
	ds_read_b64_tr_b16 v[118:119], v197 offset:0x1400
	ds_read_b64_tr_b16 v[120:121], v197 offset:0x1c00
	v_mfma_f32_32x32x16_bf16 v[48:63], v[106:109], v[122:125], v[48:63]
	ds_read_b64_tr_b16 v[122:123], v197 offset:0x2400
	ds_read_b64_tr_b16 v[124:125], v197 offset:0x2c00
	v_mfma_f32_32x32x16_bf16 v[48:63], v[110:113], v[126:129], v[48:63]
	ds_read_b64_tr_b16 v[126:127], v197 offset:0x3400
	ds_read_b64_tr_b16 v[128:129], v197 offset:0x3c00
	s_waitcnt lgkmcnt(0)
	v_mfma_f32_32x32x16_bf16 v[32:47], v[98:101], v[114:117], v[32:47]
	ds_read_b64_tr_b16 v[114:115], v197 offset:0x600
	ds_read_b64_tr_b16 v[116:117], v197 offset:0xe00
	v_mfma_f32_32x32x16_bf16 v[32:47], v[102:105], v[118:121], v[32:47]
	ds_read_b64_tr_b16 v[118:119], v197 offset:0x1600
	ds_read_b64_tr_b16 v[120:121], v197 offset:0x1e00
	v_mfma_f32_32x32x16_bf16 v[32:47], v[106:109], v[122:125], v[32:47]
	ds_read_b64_tr_b16 v[122:123], v197 offset:0x2600
	ds_read_b64_tr_b16 v[124:125], v197 offset:0x2e00
	v_mfma_f32_32x32x16_bf16 v[32:47], v[110:113], v[126:129], v[32:47]
	ds_read_b64_tr_b16 v[126:127], v197 offset:0x3600
	ds_read_b64_tr_b16 v[128:129], v197 offset:0x3e00
	s_waitcnt lgkmcnt(0)
	v_mfma_f32_32x32x16_bf16 v[16:31], v[98:101], v[114:117], v[16:31]
	v_max_f32_e32 v98, v81, v81
	v_max_f32_e32 v99, v80, v80
	v_max_f32_e32 v98, v99, v98
	v_max3_f32 v98, v98, v82, v83
	v_max3_f32 v98, v98, v84, v85
	v_max3_f32 v98, v98, v86, v87
	v_max3_f32 v98, v98, v88, v89
	v_max3_f32 v98, v98, v90, v91
	v_mfma_f32_32x32x16_bf16 v[16:31], v[102:105], v[118:121], v[16:31]
	v_max3_f32 v98, v98, v92, v93
	v_max3_f32 v98, v98, v94, v95
	v_max3_f32 v98, v98, v64, v65
	v_max3_f32 v98, v98, v66, v67
	v_max3_f32 v98, v98, v68, v69
	v_max3_f32 v98, v98, v70, v71
	v_max3_f32 v98, v98, v72, v73
	v_max3_f32 v98, v98, v74, v75
	v_mfma_f32_32x32x16_bf16 v[16:31], v[106:109], v[122:125], v[16:31]
	v_max3_f32 v98, v98, v76, v77
	v_max3_f32 v98, v98, v78, v79
	v_mov_b32_e32 v99, v98
	s_nop 1
	v_permlane32_swap_b32_e32 v98, v99
	v_max_f32_e32 v99, v99, v99
	v_max_f32_e32 v98, v98, v98
	v_max_f32_e32 v98, v98, v99
	v_sub_f32_e32 v99, v98, v168
	v_cmp_ge_f32_e32 vcc, s22, v99
	v_max_f32_e32 v99, v168, v168
	v_mfma_f32_32x32x16_bf16 v[16:31], v[110:113], v[126:129], v[16:31]
	v_max_f32_e32 v99, v99, v98
	v_sub_f32_e32 v98, v168, v99
	v_exp_f32_e32 v98, v98
	s_cmp_eq_u64 vcc, exec
	s_cselect_b64 s[4:5], -1, 0
	v_cndmask_b32_e64 v98, v98, 1.0, s[4:5]
	v_cmp_gt_f32_e32 vcc, 1.0, v98
	s_barrier
	s_cbranch_vccz .LBB0_286
	s_and_saveexec_b64 s[12:13], s[6:7]
	ds_write_b32 v194, v98 offset:128
	s_or_b64 exec, exec, s[12:13]
	s_waitcnt lgkmcnt(0)
	v_add_u32_e32 v112, v193, v182
	ds_read_b128 v[100:103], v112 offset:224
	ds_read_b128 v[104:107], v112 offset:192
	ds_read_b128 v[108:111], v112 offset:160
	ds_read_b128 v[112:115], v112 offset:128
	s_waitcnt lgkmcnt(3)
	v_pk_mul_f32 v[12:13], v[12:13], v[100:101]
	s_waitcnt lgkmcnt(2)
	v_pk_mul_f32 v[8:9], v[8:9], v[104:105]
	s_waitcnt lgkmcnt(1)
	v_pk_mul_f32 v[4:5], v[4:5], v[108:109]
	v_pk_mul_f32 v[14:15], v[14:15], v[102:103]
	v_pk_mul_f32 v[10:11], v[10:11], v[106:107]
	v_pk_mul_f32 v[6:7], v[6:7], v[110:111]
	s_waitcnt lgkmcnt(0)
	v_pk_mul_f32 v[2:3], v[2:3], v[114:115]
	v_pk_mul_f32 v[0:1], v[0:1], v[112:113]
	v_pk_mul_f32 v[60:61], v[60:61], v[100:101]
	v_pk_mul_f32 v[56:57], v[56:57], v[104:105]
	v_pk_mul_f32 v[52:53], v[52:53], v[108:109]
	v_pk_mul_f32 v[62:63], v[62:63], v[102:103]
	v_pk_mul_f32 v[58:59], v[58:59], v[106:107]
	v_pk_mul_f32 v[54:55], v[54:55], v[110:111]
	v_pk_mul_f32 v[50:51], v[50:51], v[114:115]
	v_pk_mul_f32 v[48:49], v[48:49], v[112:113]
	v_pk_mul_f32 v[44:45], v[44:45], v[100:101]
	v_pk_mul_f32 v[40:41], v[40:41], v[104:105]
	v_pk_mul_f32 v[36:37], v[36:37], v[108:109]
	v_pk_mul_f32 v[46:47], v[46:47], v[102:103]
	v_pk_mul_f32 v[42:43], v[42:43], v[106:107]
	v_pk_mul_f32 v[38:39], v[38:39], v[110:111]
	v_pk_mul_f32 v[34:35], v[34:35], v[114:115]
	v_pk_mul_f32 v[32:33], v[32:33], v[112:113]
	v_pk_mul_f32 v[28:29], v[28:29], v[100:101]
	v_pk_mul_f32 v[24:25], v[24:25], v[104:105]
	v_pk_mul_f32 v[20:21], v[20:21], v[108:109]
	v_pk_mul_f32 v[30:31], v[30:31], v[102:103]
	v_pk_mul_f32 v[26:27], v[26:27], v[106:107]
	v_pk_mul_f32 v[22:23], v[22:23], v[110:111]
	v_pk_mul_f32 v[18:19], v[18:19], v[114:115]
	v_pk_mul_f32 v[16:17], v[16:17], v[112:113]
